# speedup vs baseline: 1.0039x; 1.0039x over previous
; #define ATT_LOAD(kr, vr, t) do { const bf16_t* kp_ = KVb + (size_t)(t) * 64 * 2048 + kn_off; \
;         kr[0] = *(const u32x4*)kp_; kr[1] = *(const u32x4*)(kp_ + 32 * 2048); kr[2] = *(const u32x4*)(KPEb + (t) * 64 * 64 + kp_off); \
;         const bf16_t* vp_ = VTb + (t) * 64 + v_off; vr[0] = *(const u32x4*)vp_; vr[1] = *(const u32x4*)(vp_ + 64 * SEQ); } while (0)
; #define ATT_TILE(t, slot) do { const int rel_ = (t) - 4 * qb; if (rel_ <= (w >> 1)) { qk_softmax((t), (slot), rel_ == (w >> 1)); pv(slot); } } while (0)
; DI void attn_unit(const Params& P, LAS unsigned char* lds, int b, int h, int qb, bool dry) {
;     ...
;     ATT_LOAD(kA, vA, 0);
;     __syncthreads();
;     ATT_STORE(kA, vA, 0);
;     ATT_LOAD(kA, vA, 1);
;     __syncthreads();
;     for (int kt = 0; kt < nt; kt += 2) {
;         const bool more2 = kt + 2 < nt;
;         if (more2) ATT_LOAD(kB, vB, kt + 2);
;         ATT_TILE(kt, 0);
;         ATT_STORE(kA, vA, 1);
;         __syncthreads();
;         if (more2) ATT_LOAD(kA, vA, kt + 3);
;         ATT_TILE(kt + 1, 1);
;         if (more2) ATT_STORE(kB, vB, 0);
;         __syncthreads();
;     }
.LBB0_32:
	s_mov_b64 s[40:41], 0x100
	v_lshl_add_u64 v[190:191], v[190:191], 0, s[40:41]
	s_mov_b64 s[40:41], 0x80000
	v_add_u32_e32 v219, 0x80, v219
	v_lshl_add_u64 v[188:189], v[188:189], 0, s[96:97]
	v_lshl_add_u64 v[192:193], v[192:193], 0, s[40:41]
	s_add_i32 s20, s20, 2
	s_cmp_lt_u32 s20, s59
	s_cbranch_scc0 .Lattn_pfB1_skip
	v_add_co_u32_e32 v64, vcc, 0xfffa0000, v192
	s_nop 1
	v_addc_co_u32_e32 v65, vcc, -1, v193, vcc
	v_add_co_u32_e32 v66, vcc, 0xfffc0000, v192
	s_nop 1
	v_addc_co_u32_e32 v67, vcc, -1, v193, vcc
	global_load_dwordx4 v[164:167], v[64:65], off
	global_load_dwordx4 v[168:171], v[66:67], off
	v_add_co_u32_e32 v64, vcc, 0xffffe000, v188
	s_nop 1
	v_addc_co_u32_e32 v65, vcc, -1, v189, vcc
	global_load_dwordx4 v[172:175], v[64:65], off
	v_add_co_u32_e32 v64, vcc, 0xffdfff80, v190
	s_nop 1
	v_addc_co_u32_e32 v65, vcc, -1, v191, vcc
	v_add_co_u32_e32 v66, vcc, 0xffffff80, v190
	s_nop 1
	v_addc_co_u32_e32 v67, vcc, -1, v191, vcc
	global_load_dwordx4 v[176:179], v[64:65], off
	global_load_dwordx4 v[180:183], v[66:67], off
.Lattn_pfB1_skip:
	s_andn2_b64 vcc, exec, s[50:51]
	s_waitcnt lgkmcnt(0)
	s_barrier
	s_cbranch_vccz .LBB0_51

; #define ATT_LOAD(kr, vr, t) do { const bf16_t* kp_ = KVb + (size_t)(t) * 64 * 2048 + kn_off; \
;         kr[0] = *(const u32x4*)kp_; kr[1] = *(const u32x4*)(kp_ + 32 * 2048); kr[2] = *(const u32x4*)(KPEb + (t) * 64 * 64 + kp_off); \
;         const bf16_t* vp_ = VTb + (t) * 64 + v_off; vr[0] = *(const u32x4*)vp_; vr[1] = *(const u32x4*)(vp_ + 64 * SEQ); } while (0)
; #define ATT_TILE(t, slot) do { const int rel_ = (t) - 4 * qb; if (rel_ <= (w >> 1)) { qk_softmax((t), (slot), rel_ == (w >> 1)); pv(slot); } } while (0)
; DI void attn_unit(const Params& P, LAS unsigned char* lds, int b, int h, int qb, bool dry) {
;     ...
;     ATT_LOAD(kA, vA, 0);
;     __syncthreads();
;     ATT_STORE(kA, vA, 0);
;     ATT_LOAD(kA, vA, 1);
;     __syncthreads();
;     for (int kt = 0; kt < nt; kt += 2) {
;         const bool more2 = kt + 2 < nt;
;         if (more2) ATT_LOAD(kB, vB, kt + 2);
;         ATT_TILE(kt, 0);
;         ATT_STORE(kA, vA, 1);
;         __syncthreads();
;         if (more2) ATT_LOAD(kA, vA, kt + 3);
;         ATT_TILE(kt + 1, 1);
.Lattn_wdone0:
	s_not_b64 s[40:41], s[52:53]
	s_mov_b64 vcc, s[52:53]
	s_cbranch_vccz .Lattn_pfA1_skip
	v_add_co_u32_e32 v64, vcc, 0xfffe0000, v192
	s_nop 1
	v_addc_co_u32_e32 v65, vcc, -1, v193, vcc
	global_load_dwordx4 v[144:147], v[64:65], off
	global_load_dwordx4 v[148:151], v[192:193], off
	global_load_dwordx4 v[152:155], v[188:189], off
	v_add_co_u32_e32 v64, vcc, 0xffe00000, v190
	s_nop 1
	v_addc_co_u32_e32 v65, vcc, -1, v191, vcc
	global_load_dwordx4 v[156:159], v[64:65], off
	global_load_dwordx4 v[160:163], v[190:191], off
.Lattn_pfA1_skip:
	s_andn2_b64 vcc, exec, s[52:53]
	s_waitcnt lgkmcnt(0)
	s_barrier
	s_cbranch_vccnz .LBB0_44
	s_add_i32 s80, s80, -1
	s_cmp_gt_i32 s80, s26
	s_cbranch_scc0 .LBB0_45

; #define ATT_LOAD(kr, vr, t) do { const bf16_t* kp_ = KVb + (size_t)(t) * 64 * 2048 + kn_off; \
;         kr[0] = *(const u32x4*)kp_; kr[1] = *(const u32x4*)(kp_ + 32 * 2048); kr[2] = *(const u32x4*)(KPEb + (t) * 64 * 64 + kp_off); \
;         const bf16_t* vp_ = VTb + (t) * 64 + v_off; vr[0] = *(const u32x4*)vp_; vr[1] = *(const u32x4*)(vp_ + 64 * SEQ); } while (0)
; #define ATT_TILE(t, slot) do { const int rel_ = (t) - 4 * qb; if (rel_ <= (w >> 1)) { qk_softmax((t), (slot), rel_ == (w >> 1)); pv(slot); } } while (0)
; DI void attn_unit(const Params& P, LAS unsigned char* lds, int b, int h, int qb, bool dry) {
;     ...
;     ATT_LOAD(kA, vA, 0);
;     __syncthreads();
;     ATT_STORE(kA, vA, 0);
;     ATT_LOAD(kA, vA, 1);
;     __syncthreads();
;     for (int kt = 0; kt < nt; kt += 2) {
;         const bool more2 = kt + 2 < nt;
;         if (more2) ATT_LOAD(kB, vB, kt + 2);
;         ATT_TILE(kt, 0);
;         ATT_STORE(kA, vA, 1);
;         __syncthreads();
;         if (more2) ATT_LOAD(kA, vA, kt + 3);
;         ATT_TILE(kt + 1, 1);
;         if (more2) ATT_STORE(kB, vB, 0);
;         __syncthreads();
;     }
.LBB0_52:
	s_mov_b64 s[30:31], 0x100
	v_lshl_add_u64 v[190:191], v[190:191], 0, s[30:31]
	s_mov_b64 s[30:31], 0x80000
	v_add_u32_e32 v219, 0x80, v219
	v_lshl_add_u64 v[188:189], v[188:189], 0, s[96:97]
	v_lshl_add_u64 v[192:193], v[192:193], 0, s[30:31]
	s_add_i32 s20, s20, 2
	s_cmp_lt_u32 s20, s35
	s_cbranch_scc0 .Lattn_pfB2_skip
	v_add_co_u32_e32 v64, vcc, 0xfffa0000, v192
	s_nop 1
	v_addc_co_u32_e32 v65, vcc, -1, v193, vcc
	v_add_co_u32_e32 v66, vcc, 0xfffc0000, v192
	s_nop 1
	v_addc_co_u32_e32 v67, vcc, -1, v193, vcc
	global_load_dwordx4 v[164:167], v[64:65], off
	global_load_dwordx4 v[168:171], v[66:67], off
	v_add_co_u32_e32 v64, vcc, 0xffffe000, v188
	s_nop 1
	v_addc_co_u32_e32 v65, vcc, -1, v189, vcc
	global_load_dwordx4 v[172:175], v[64:65], off
	v_add_co_u32_e32 v64, vcc, 0xffdfff80, v190
	s_nop 1
	v_addc_co_u32_e32 v65, vcc, -1, v191, vcc
	v_add_co_u32_e32 v66, vcc, 0xffffff80, v190
	s_nop 1
	v_addc_co_u32_e32 v67, vcc, -1, v191, vcc
	global_load_dwordx4 v[176:179], v[64:65], off
	global_load_dwordx4 v[180:183], v[66:67], off
.Lattn_pfB2_skip:
	s_andn2_b64 vcc, exec, s[2:3]
	s_waitcnt lgkmcnt(0)
	s_barrier
	s_cbranch_vccz .LBB0_30

; #define ATT_LOAD(kr, vr, t) do { const bf16_t* kp_ = KVb + (size_t)(t) * 64 * 2048 + kn_off; \
;         kr[0] = *(const u32x4*)kp_; kr[1] = *(const u32x4*)(kp_ + 32 * 2048); kr[2] = *(const u32x4*)(KPEb + (t) * 64 * 64 + kp_off); \
;         const bf16_t* vp_ = VTb + (t) * 64 + v_off; vr[0] = *(const u32x4*)vp_; vr[1] = *(const u32x4*)(vp_ + 64 * SEQ); } while (0)
; #define ATT_TILE(t, slot) do { const int rel_ = (t) - 4 * qb; if (rel_ <= (w >> 1)) { qk_softmax((t), (slot), rel_ == (w >> 1)); pv(slot); } } while (0)
; DI void attn_unit(const Params& P, LAS unsigned char* lds, int b, int h, int qb, bool dry) {
;     ...
;     ATT_LOAD(kA, vA, 0);
;     __syncthreads();
;     ATT_STORE(kA, vA, 0);
;     ATT_LOAD(kA, vA, 1);
;     __syncthreads();
;     for (int kt = 0; kt < nt; kt += 2) {
;         const bool more2 = kt + 2 < nt;
;         if (more2) ATT_LOAD(kB, vB, kt + 2);
;         ATT_TILE(kt, 0);
;         ATT_STORE(kA, vA, 1);
;         __syncthreads();
;         if (more2) ATT_LOAD(kA, vA, kt + 3);
;         ATT_TILE(kt + 1, 1);
.Lattn_wdone2:
	s_not_b64 s[40:41], s[30:31]
	s_mov_b64 vcc, s[30:31]
	s_cbranch_vccz .Lattn_pfA2_skip
	v_add_co_u32_e32 v64, vcc, 0xfffe0000, v192
	s_nop 1
	v_addc_co_u32_e32 v65, vcc, -1, v193, vcc
	global_load_dwordx4 v[144:147], v[64:65], off
	global_load_dwordx4 v[148:151], v[192:193], off
	global_load_dwordx4 v[152:155], v[188:189], off
	v_add_co_u32_e32 v64, vcc, 0xffe00000, v190
	s_nop 1
	v_addc_co_u32_e32 v65, vcc, -1, v191, vcc
	global_load_dwordx4 v[156:159], v[64:65], off
	global_load_dwordx4 v[160:163], v[190:191], off
.Lattn_pfA2_skip:
	s_andn2_b64 vcc, exec, s[30:31]
	s_waitcnt lgkmcnt(0)
	s_barrier
	s_cbranch_vccnz .LBB0_64
	s_add_i32 s37, s37, -1
	s_cmp_gt_i32 s37, s36
	s_cbranch_scc0 .LBB0_65
